# NSA compressed-branch PV: all 15 V-tile loads issued up front into 8 free VGPR tiles with counted vmcnt instead of 3-deep rotation (on top of gate hoisting)
# baseline (speedup 1.0000x reference)
.Lnsa_ready:
	s_lshr_b32 s2, s40, 1
	s_and_b32 s2, s2, 0xfc
	s_and_b32 s3, s40, 3
	s_or_b32 s2, s2, s3
	s_xor_b32 s86, s2, 0xfc
	s_lshr_b32 s0, s40, 9
	v_readlane_b32 s1, v254, 63
	s_lshl_b32 s89, s86, 3
	s_waitcnt vmcnt(3)
	v_bfe_u32 v129, v188, 2, 3
	s_or_b32 s0, s0, s1
	v_or_b32_e32 v197, s89, v129
	s_bfe_u32 s1, s40, 0x10002
	v_and_b32_e32 v130, 3, v188
	v_lshl_or_b32 v148, s0, 11, v197
	s_lshl_b32 s0, s0, 1
	v_lshl_or_b32 v128, s1, 2, v130
	s_or_b32 s36, s0, s1
	v_mov_b32_e32 v149, v1
	v_readlane_b32 s0, v254, 61
	v_lshlrev_b64 v[2:3], 10, v[148:149]
	v_readlane_b32 s1, v254, 62
	v_readlane_b32 s2, v254, 57
	v_lshlrev_b32_e32 v154, 3, v188
	v_lshl_add_u64 v[2:3], s[0:1], 0, v[2:3]
	s_lshl_b64 s[0:1], s[36:37], 14
	s_add_u32 s4, s2, s0
	v_readlane_b32 s2, v254, 55
	v_ashrrev_i32_e32 v155, 31, v154
	s_addc_u32 s5, s2, s1
	v_lshlrev_b64 v[152:153], 1, v[154:155]
	v_lshl_add_u64 v[42:43], s[4:5], 0, v[152:153]
	s_movk_i32 s2, 0x2000
	v_add_co_u32_e32 v46, vcc, s2, v42
	v_lshlrev_b32_e32 v0, 7, v128
	s_nop 0
	v_addc_co_u32_e32 v47, vcc, 0, v43, vcc
	v_lshl_add_u64 v[6:7], v[2:3], 0, v[0:1]
	global_load_dwordx4 v[2:5], v[46:47], off offset:-4096
	v_lshlrev_b32_e32 v8, 3, v196
	v_ashrrev_i32_e32 v9, 31, v8
	v_lshl_add_u64 v[52:53], v[8:9], 1, v[6:7]
	global_load_dwordx4 v[80:83], v[52:53], off
	global_load_dwordx4 v[18:21], v[42:43], off
	s_movk_i32 s3, 0x1000
	v_add_co_u32_e32 v50, vcc, s3, v42
	global_load_dwordx4 v[84:87], v[52:53], off offset:32
	s_nop 0
	v_addc_co_u32_e32 v51, vcc, 0, v43, vcc
	global_load_dwordx4 v[38:41], v[50:51], off offset:1024
	v_readlane_b32 s4, v254, 59
	v_readlane_b32 s5, v254, 60
	global_load_dwordx4 v[54:57], v[42:43], off offset:1024
	global_load_dwordx4 v[58:61], v[42:43], off offset:2048
	v_mov_b64_e32 v[6:7], s[4:5]
	s_movk_i32 s4, 0x60
	v_mad_u64_u32 v[6:7], s[4:5], v148, s4, v[6:7]
	v_readlane_b32 s4, v254, 53
	s_add_u32 s0, s4, s0
	v_readlane_b32 s4, v254, 51
	v_mul_u32_u24_e32 v0, 3, v128
	s_addc_u32 s1, s4, s1
	v_lshlrev_b32_e32 v0, 2, v0
	v_lshl_add_u64 v[48:49], s[0:1], 0, v[152:153]
	s_movk_i32 s0, 0x3000
	v_lshl_add_u64 v[150:151], v[6:7], 0, v[0:1]
	v_add_co_u32_e32 v44, vcc, s0, v48
	v_lshlrev_b32_e32 v66, 6, v196
	s_nop 0
	v_addc_co_u32_e32 v45, vcc, 0, v49, vcc
	global_load_dword v0, v[150:151], off
	global_load_dword v234, v[150:151], off offset:4
	global_load_dwordx4 v[34:37], v[44:45], off offset:3072
	global_load_dwordx4 v[88:91], v[52:53], off offset:64
	global_load_dwordx4 v[62:65], v[42:43], off offset:3072
	global_load_dwordx4 v[92:95], v[52:53], off offset:96
	v_or_b32_e32 v67, 31, v66
	v_or_b32_e32 v68, 47, v66
	v_cmp_le_i32_e32 vcc, v67, v197
	v_or_b32_e32 v69, 63, v66
	v_add_u32_e32 v70, 0x4f, v66
	v_add_u32_e32 v71, 0x9f, v66
	v_add_u32_e32 v72, 0xaf, v66
	v_add_u32_e32 v73, 0xbf, v66
	v_add_u32_e32 v74, 0xcf, v66
	v_add_u32_e32 v75, 0x19f, v66
	v_add_u32_e32 v76, 0x1af, v66
	v_lshl_add_u32 v206, v188, 2, s83
	v_cmp_eq_u32_e64 s[8:9], 0, v130
	s_waitcnt vmcnt(9)
	v_mfma_f32_32x32x16_bf16 v[18:33], v[18:21], v[80:83], 0
	v_mfma_f32_32x32x16_bf16 v[2:17], v[2:5], v[80:83], 0
	s_waitcnt vmcnt(7)
	v_mfma_f32_32x32x16_bf16 v[2:17], v[38:41], v[84:87], v[2:17]
	global_load_dwordx4 v[38:41], v[50:51], off offset:2048
	s_nop 0
	global_load_dwordx4 v[50:53], v[50:51], off offset:3072
	s_waitcnt vmcnt(8)
	v_mfma_f32_32x32x16_bf16 v[18:33], v[54:57], v[84:87], v[18:33]
	global_load_dwordx4 v[54:57], v[46:47], off
	s_waitcnt vmcnt(5)
	v_mfma_f32_32x32x16_bf16 v[18:33], v[58:61], v[88:91], v[18:33]
	v_add_u32_e32 v58, 0x11f, v66
	v_add_u32_e32 v59, 0x12f, v66
	v_add_u32_e32 v60, 0x13f, v66
	v_add_u32_e32 v61, 0x14f, v66
	s_waitcnt vmcnt(3)
	v_mfma_f32_32x32x16_bf16 v[18:33], v[62:65], v[92:95], v[18:33]
	s_waitcnt vmcnt(2)
	v_mfma_f32_32x32x16_bf16 v[2:17], v[38:41], v[88:91], v[2:17]
	s_nop 9
	v_mul_f32_e32 v18, 0x3e38aa3b, v18
	v_mul_f32_e32 v19, 0x3e38aa3b, v19
	v_cndmask_b32_e32 v62, v239, v18, vcc
	v_cmp_le_i32_e32 vcc, v68, v197
	v_mul_f32_e32 v20, 0x3e38aa3b, v20
	v_mul_f32_e32 v21, 0x3e38aa3b, v21
	v_cndmask_b32_e32 v63, v239, v19, vcc
	v_cmp_le_i32_e32 vcc, v69, v197
	v_mul_f32_e32 v22, 0x3e38aa3b, v22
	v_mul_f32_e32 v23, 0x3e38aa3b, v23
	v_cndmask_b32_e32 v64, v239, v20, vcc
	v_cmp_le_i32_e32 vcc, v70, v197
	v_mul_f32_e32 v24, 0x3e38aa3b, v24
	v_mul_f32_e32 v25, 0x3e38aa3b, v25
	v_cndmask_b32_e32 v65, v239, v21, vcc
	v_cmp_le_i32_e32 vcc, v71, v197
	v_mul_f32_e32 v26, 0x3e38aa3b, v26
	v_mul_f32_e32 v27, 0x3e38aa3b, v27
	v_cndmask_b32_e32 v67, v239, v22, vcc
	v_cmp_le_i32_e32 vcc, v72, v197
	v_mul_f32_e32 v28, 0x3e38aa3b, v28
	global_load_dwordx4 v[38:41], v[46:47], off offset:2048
	v_cndmask_b32_e32 v68, v239, v23, vcc
	v_cmp_le_i32_e32 vcc, v73, v197
	s_waitcnt vmcnt(2)
	v_mfma_f32_32x32x16_bf16 v[2:17], v[50:53], v[92:95], v[2:17]
	v_mul_f32_e32 v29, 0x3e38aa3b, v29
	v_cndmask_b32_e32 v69, v239, v24, vcc
	v_cmp_le_i32_e32 vcc, v74, v197
	v_mul_f32_e32 v30, 0x3e38aa3b, v30
	v_mul_f32_e32 v31, 0x3e38aa3b, v31
	v_cndmask_b32_e32 v70, v239, v25, vcc
	v_cmp_le_i32_e32 vcc, v58, v197
	v_add_u32_e32 v19, 0x1bf, v66
	global_load_dwordx4 v[50:53], v[46:47], off offset:3072
	v_cndmask_b32_e32 v71, v239, v26, vcc
	v_cmp_le_i32_e32 vcc, v59, v197
	v_mul_f32_e32 v20, 0x3e38aa3b, v32
	v_mul_f32_e32 v2, 0x3e38aa3b, v2
	v_cndmask_b32_e32 v72, v239, v27, vcc
	v_cmp_le_i32_e32 vcc, v60, v197
	v_max3_f32 v18, v62, s69, v63
	v_max3_f32 v18, v18, v64, v65
	v_cndmask_b32_e32 v73, v239, v28, vcc
	v_cmp_le_i32_e32 vcc, v61, v197
	global_load_dwordx4 v[58:61], v[46:47], off offset:1024
	v_mul_f32_e32 v3, 0x3e38aa3b, v3
	v_cndmask_b32_e32 v74, v239, v29, vcc
	v_cmp_le_i32_e32 vcc, v75, v197
	v_max3_f32 v18, v18, v67, v68
	v_max3_f32 v18, v18, v69, v70
	v_cndmask_b32_e32 v75, v239, v30, vcc
	v_cmp_le_i32_e32 vcc, v76, v197
	v_mul_f32_e32 v4, 0x3e38aa3b, v4
	v_max3_f32 v18, v18, v71, v72
	v_cndmask_b32_e32 v76, v239, v31, vcc
	v_cmp_le_i32_e32 vcc, v19, v197
	v_add_u32_e32 v19, 0x1cf, v66
	v_max3_f32 v18, v18, v73, v74
	v_cndmask_b32_e32 v77, v239, v20, vcc
	v_mul_f32_e32 v20, 0x3e38aa3b, v33
	v_cmp_le_i32_e32 vcc, v19, v197
	v_add_u32_e32 v19, 0x21f, v66
	v_max3_f32 v18, v18, v75, v76
	v_cndmask_b32_e32 v78, v239, v20, vcc
	v_cmp_le_i32_e32 vcc, v19, v197
	v_max3_f32 v18, v18, v77, v78
	s_nop 0
	v_cndmask_b32_e32 v46, v239, v2, vcc
	v_add_u32_e32 v2, 0x22f, v66
	v_cmp_le_i32_e32 vcc, v2, v197
	s_nop 1
	v_cndmask_b32_e32 v47, v239, v3, vcc
	v_add_u32_e32 v3, 0x23f, v66
	v_cmp_le_i32_e32 vcc, v3, v197
	v_add_u32_e32 v3, 0x24f, v66
	v_max3_f32 v2, v18, v46, v47
	v_cndmask_b32_e32 v96, v239, v4, vcc
	v_mul_f32_e32 v4, 0x3e38aa3b, v5
	v_cmp_le_i32_e32 vcc, v3, v197
	v_add_u32_e32 v3, 0x29f, v66
	s_waitcnt vmcnt(3)
	v_mfma_f32_32x32x16_bf16 v[18:33], v[54:57], v[80:83], 0
	v_cndmask_b32_e32 v97, v239, v4, vcc
	v_mul_f32_e32 v4, 0x3e38aa3b, v6
	v_cmp_le_i32_e32 vcc, v3, v197
	v_add_u32_e32 v3, 0x2af, v66
	v_max3_f32 v2, v2, v96, v97
	v_cndmask_b32_e32 v100, v239, v4, vcc
	v_mul_f32_e32 v4, 0x3e38aa3b, v7
	v_cmp_le_i32_e32 vcc, v3, v197
	v_add_u32_e32 v3, 0x2bf, v66
	s_waitcnt vmcnt(0)
	v_mfma_f32_32x32x16_bf16 v[18:33], v[58:61], v[84:87], v[18:33]
	v_cndmask_b32_e32 v101, v239, v4, vcc
	v_mul_f32_e32 v4, 0x3e38aa3b, v8
	v_cmp_le_i32_e32 vcc, v3, v197
	v_add_u32_e32 v3, 0x2cf, v66
	v_max3_f32 v2, v2, v100, v101
	v_cndmask_b32_e32 v102, v239, v4, vcc
	v_mul_f32_e32 v4, 0x3e38aa3b, v9
	v_cmp_le_i32_e32 vcc, v3, v197
	v_add_u32_e32 v3, 0x31f, v66
	v_mfma_f32_32x32x16_bf16 v[18:33], v[38:41], v[88:91], v[18:33]
	v_cndmask_b32_e32 v103, v239, v4, vcc
	v_mul_f32_e32 v4, 0x3e38aa3b, v10
	v_cmp_le_i32_e32 vcc, v3, v197
	v_add_u32_e32 v3, 0x32f, v66
	v_max3_f32 v2, v2, v102, v103
	v_cndmask_b32_e32 v104, v239, v4, vcc
	v_mul_f32_e32 v4, 0x3e38aa3b, v11
	v_cmp_le_i32_e32 vcc, v3, v197
	v_mul_f32_e32 v3, 0x3e38aa3b, v12
	v_mfma_f32_32x32x16_bf16 v[18:33], v[50:53], v[92:95], v[18:33]
	v_cndmask_b32_e32 v105, v239, v4, vcc
	v_max3_f32 v8, v2, v104, v105
	v_add_u32_e32 v2, 0x33f, v66
	v_cmp_le_i32_e32 vcc, v2, v197
	v_add_u32_e32 v2, 0x34f, v66
	v_add_u32_e32 v9, 0x39f, v66
	v_cndmask_b32_e32 v106, v239, v3, vcc
	v_mul_f32_e32 v3, 0x3e38aa3b, v13
	v_cmp_le_i32_e32 vcc, v2, v197
	v_mul_f32_e32 v10, 0x3e38aa3b, v14
	s_nop 1
	v_mul_f32_e32 v29, 0x3e38aa3b, v29
	v_cndmask_b32_e32 v107, v239, v3, vcc
	v_add_co_u32_e32 v6, vcc, s0, v42
	v_max3_f32 v8, v8, v106, v107
	s_nop 0
	v_addc_co_u32_e32 v7, vcc, 0, v43, vcc
	global_load_dwordx4 v[2:5], v[6:7], off
	global_load_dwordx4 v[54:57], v[6:7], off offset:1024
	global_load_dwordx4 v[58:61], v[6:7], off offset:2048
	global_load_dwordx4 v[38:41], v[6:7], off offset:3072
	v_cmp_le_i32_e32 vcc, v9, v197
	v_add_u32_e32 v9, 0x3af, v66
	v_add_u32_e32 v7, 0x41f, v66
	v_cndmask_b32_e32 v108, v239, v10, vcc
	v_mul_f32_e32 v10, 0x3e38aa3b, v15
	v_cmp_le_i32_e32 vcc, v9, v197
	v_add_u32_e32 v9, 0x3bf, v66
	v_mul_f32_e32 v30, 0x3e38aa3b, v30
	v_cndmask_b32_e32 v109, v239, v10, vcc
	v_mul_f32_e32 v10, 0x3e38aa3b, v16
	v_cmp_le_i32_e32 vcc, v9, v197
	v_add_u32_e32 v9, 0x3cf, v66
	v_max3_f32 v8, v8, v108, v109
	v_cndmask_b32_e32 v110, v239, v10, vcc
	v_mul_f32_e32 v10, 0x3e38aa3b, v17
	v_cmp_le_i32_e32 vcc, v9, v197
	v_mul_f32_e32 v31, 0x3e38aa3b, v31
	v_mul_f32_e32 v32, 0x3e38aa3b, v32
	v_cndmask_b32_e32 v111, v239, v10, vcc
	v_max3_f32 v6, v8, v110, v111
	v_mul_f32_e32 v8, 0x3e38aa3b, v18
	v_cmp_le_i32_e32 vcc, v7, v197
	v_add_u32_e32 v7, 0x42f, v66
	v_mul_f32_e32 v33, 0x3e38aa3b, v33
	v_cndmask_b32_e32 v50, v239, v8, vcc
	v_mul_f32_e32 v8, 0x3e38aa3b, v19
	v_cmp_le_i32_e32 vcc, v7, v197
	v_add_u32_e32 v7, 0x43f, v66
	v_add_u32_e32 v19, 0x54f, v66
	v_cndmask_b32_e32 v51, v239, v8, vcc
	v_mul_f32_e32 v8, 0x3e38aa3b, v20
	v_cmp_le_i32_e32 vcc, v7, v197
	v_add_u32_e32 v7, 0x44f, v66
	v_max3_f32 v6, v6, v50, v51
	v_cndmask_b32_e32 v20, v239, v8, vcc
	v_mul_f32_e32 v8, 0x3e38aa3b, v21
	v_cmp_le_i32_e32 vcc, v7, v197
	v_add_u32_e32 v7, 0x49f, v66
	s_nop 0
	v_cndmask_b32_e32 v21, v239, v8, vcc
	v_mul_f32_e32 v8, 0x3e38aa3b, v22
	v_cmp_le_i32_e32 vcc, v7, v197
	v_add_u32_e32 v7, 0x4af, v66
	v_max3_f32 v6, v6, v20, v21
	v_cndmask_b32_e32 v22, v239, v8, vcc
	v_mul_f32_e32 v8, 0x3e38aa3b, v23
	v_cmp_le_i32_e32 vcc, v7, v197
	v_add_u32_e32 v7, 0x4bf, v66
	s_nop 0
	v_cndmask_b32_e32 v23, v239, v8, vcc
	v_mul_f32_e32 v8, 0x3e38aa3b, v24
	v_cmp_le_i32_e32 vcc, v7, v197
	v_add_u32_e32 v7, 0x4cf, v66
	v_max3_f32 v6, v6, v22, v23
	v_cndmask_b32_e32 v24, v239, v8, vcc
	v_mul_f32_e32 v8, 0x3e38aa3b, v25
	v_cmp_le_i32_e32 vcc, v7, v197
	v_add_u32_e32 v7, 0x51f, v66
	s_nop 0
	v_cndmask_b32_e32 v25, v239, v8, vcc
	v_mul_f32_e32 v8, 0x3e38aa3b, v26
	v_cmp_le_i32_e32 vcc, v7, v197
	v_add_u32_e32 v7, 0x52f, v66
	v_max3_f32 v6, v6, v24, v25
	v_cndmask_b32_e32 v26, v239, v8, vcc
	v_mul_f32_e32 v8, 0x3e38aa3b, v27
	v_cmp_le_i32_e32 vcc, v7, v197
	v_mul_f32_e32 v7, 0x3e38aa3b, v28
	s_nop 0
	v_cndmask_b32_e32 v27, v239, v8, vcc
	v_max3_f32 v18, v6, v26, v27
	v_add_u32_e32 v6, 0x53f, v66
	v_cmp_le_i32_e32 vcc, v6, v197
	s_nop 1
	v_cndmask_b32_e32 v28, v239, v7, vcc
	s_waitcnt vmcnt(3)
	v_mfma_f32_32x32x16_bf16 v[2:17], v[2:5], v[80:83], 0
	v_cmp_le_i32_e32 vcc, v19, v197
	v_add_u32_e32 v19, 0x59f, v66
	s_nop 0
	v_cndmask_b32_e32 v29, v239, v29, vcc
	v_cmp_le_i32_e32 vcc, v19, v197
	v_add_u32_e32 v19, 0x5af, v66
	v_max3_f32 v18, v18, v28, v29
	s_waitcnt vmcnt(2)
	v_mfma_f32_32x32x16_bf16 v[2:17], v[54:57], v[84:87], v[2:17]
	v_cndmask_b32_e32 v30, v239, v30, vcc
	v_cmp_le_i32_e32 vcc, v19, v197
	v_add_u32_e32 v19, 0x5bf, v66
	s_nop 0
	v_cndmask_b32_e32 v31, v239, v31, vcc
	v_cmp_le_i32_e32 vcc, v19, v197
	v_add_u32_e32 v19, 0x5cf, v66
	s_waitcnt vmcnt(1)
	v_mfma_f32_32x32x16_bf16 v[2:17], v[58:61], v[88:91], v[2:17]
	v_cndmask_b32_e32 v32, v239, v32, vcc
	v_cmp_le_i32_e32 vcc, v19, v197
	v_add_u32_e32 v19, 0x61f, v66
	v_max3_f32 v18, v18, v30, v31
	v_cndmask_b32_e32 v33, v239, v33, vcc
	v_cmp_le_i32_e32 vcc, v19, v197
	v_max3_f32 v18, v18, v32, v33
	s_waitcnt vmcnt(0)
	v_mfma_f32_32x32x16_bf16 v[2:17], v[38:41], v[92:95], v[2:17]
	s_nop 11
	v_mul_f32_e32 v2, 0x3e38aa3b, v2
	v_cndmask_b32_e32 v114, v239, v2, vcc
	v_add_u32_e32 v2, 0x62f, v66
	v_mul_f32_e32 v3, 0x3e38aa3b, v3
	v_cmp_le_i32_e32 vcc, v2, v197
	v_mul_f32_e32 v4, 0x3e38aa3b, v4
	s_nop 0
	v_cndmask_b32_e32 v115, v239, v3, vcc
	v_add_u32_e32 v3, 0x63f, v66
	v_cmp_le_i32_e32 vcc, v3, v197
	v_add_u32_e32 v3, 0x64f, v66
	v_max3_f32 v2, v18, v114, v115
	v_cndmask_b32_e32 v116, v239, v4, vcc
	v_mul_f32_e32 v4, 0x3e38aa3b, v5
	v_cmp_le_i32_e32 vcc, v3, v197
	v_add_u32_e32 v3, 0x69f, v66
	s_nop 0
	v_cndmask_b32_e32 v117, v239, v4, vcc
	v_mul_f32_e32 v4, 0x3e38aa3b, v6
	v_cmp_le_i32_e32 vcc, v3, v197
	v_add_u32_e32 v3, 0x6af, v66
	v_max3_f32 v2, v2, v116, v117
	v_cndmask_b32_e32 v120, v239, v4, vcc
	v_mul_f32_e32 v4, 0x3e38aa3b, v7
	v_cmp_le_i32_e32 vcc, v3, v197
	v_add_u32_e32 v3, 0x6bf, v66
	s_nop 0
	v_cndmask_b32_e32 v121, v239, v4, vcc
	v_mul_f32_e32 v4, 0x3e38aa3b, v8
	v_cmp_le_i32_e32 vcc, v3, v197
	v_add_u32_e32 v3, 0x6cf, v66
	v_max3_f32 v2, v2, v120, v121
	v_cndmask_b32_e32 v122, v239, v4, vcc
	v_mul_f32_e32 v4, 0x3e38aa3b, v9
	v_cmp_le_i32_e32 vcc, v3, v197
	v_add_u32_e32 v3, 0x71f, v66
	s_nop 0
	v_cndmask_b32_e32 v123, v239, v4, vcc
	v_mul_f32_e32 v4, 0x3e38aa3b, v10
	v_cmp_le_i32_e32 vcc, v3, v197
	v_add_u32_e32 v3, 0x72f, v66
	v_max3_f32 v2, v2, v122, v123
	v_cndmask_b32_e32 v132, v239, v4, vcc
	v_mul_f32_e32 v4, 0x3e38aa3b, v11
	v_cmp_le_i32_e32 vcc, v3, v197
	v_add_u32_e32 v3, 0x73f, v66
	s_nop 0
	v_cndmask_b32_e32 v133, v239, v4, vcc
	v_mul_f32_e32 v4, 0x3e38aa3b, v12
	v_cmp_le_i32_e32 vcc, v3, v197
	v_add_u32_e32 v3, 0x74f, v66
	v_max3_f32 v2, v2, v132, v133
	v_cndmask_b32_e32 v134, v239, v4, vcc
	v_mul_f32_e32 v4, 0x3e38aa3b, v13
	v_cmp_le_i32_e32 vcc, v3, v197
	v_add_u32_e32 v3, 0x79f, v66
	s_nop 0
	v_cndmask_b32_e32 v135, v239, v4, vcc
	v_mul_f32_e32 v4, 0x3e38aa3b, v14
	v_cmp_le_i32_e32 vcc, v3, v197
	v_add_u32_e32 v3, 0x7af, v66
	v_max3_f32 v2, v2, v134, v135
	v_cndmask_b32_e32 v14, v239, v4, vcc
	v_mul_f32_e32 v4, 0x3e38aa3b, v15
	v_cmp_le_i32_e32 vcc, v3, v197
	v_add_u32_e32 v3, 0x7bf, v66
	s_nop 0
	v_cndmask_b32_e32 v15, v239, v4, vcc
	v_mul_f32_e32 v4, 0x3e38aa3b, v16
	v_cmp_le_i32_e32 vcc, v3, v197
	v_add_u32_e32 v3, 0x7cf, v66
	v_max3_f32 v2, v2, v14, v15
	v_cndmask_b32_e32 v16, v239, v4, vcc
	v_mul_f32_e32 v4, 0x3e38aa3b, v17
	v_cmp_le_i32_e32 vcc, v3, v197
	v_xor_b32_e32 v3, 32, v235
	s_nop 0
	v_cndmask_b32_e32 v17, v239, v4, vcc
	v_and_b32_e32 v4, 64, v235
	v_add_u32_e32 v131, 64, v4
	v_cmp_lt_i32_e32 vcc, v3, v131
	v_max3_f32 v2, v2, v16, v17
	s_nop 0
	v_cndmask_b32_e32 v3, v235, v3, vcc
	v_lshlrev_b32_e32 v205, 2, v3
	ds_bpermute_b32 v3, v205, v2
	s_waitcnt lgkmcnt(0)
	v_max_f32_e32 v3, v3, v3
	v_max_f32_e32 v2, v2, v3
	v_cmp_neq_f32_e32 vcc, s69, v2
	s_nop 1
	v_cndmask_b32_e32 v136, 0, v2, vcc
	v_sub_f32_e32 v2, v62, v136
	v_exp_f32_e32 v2, v2
	v_sub_f32_e32 v3, v63, v136
	v_exp_f32_e32 v3, v3
	v_sub_f32_e32 v4, v64, v136
	v_exp_f32_e32 v4, v4
	v_sub_f32_e32 v5, v65, v136
	v_exp_f32_e32 v5, v5
	v_add_f32_e32 v6, 0, v2
	v_add_f32_e32 v6, v3, v6
	v_add_f32_e32 v6, v4, v6
	v_add_f32_e32 v10, v5, v6
	v_sub_f32_e32 v6, v67, v136
	v_exp_f32_e32 v6, v6
	v_sub_f32_e32 v7, v68, v136
	v_exp_f32_e32 v7, v7
	v_sub_f32_e32 v8, v69, v136
	v_exp_f32_e32 v8, v8
	v_sub_f32_e32 v9, v70, v136
	v_exp_f32_e32 v9, v9
	v_sub_f32_e32 v11, v71, v136
	v_add_f32_e32 v10, v6, v10
	v_exp_f32_e32 v18, v11
	v_sub_f32_e32 v11, v72, v136
	v_add_f32_e32 v10, v7, v10
	v_exp_f32_e32 v19, v11
	v_sub_f32_e32 v11, v73, v136
	v_add_f32_e32 v10, v8, v10
	v_exp_f32_e32 v38, v11
	v_sub_f32_e32 v11, v74, v136
	v_add_f32_e32 v10, v9, v10
	v_exp_f32_e32 v39, v11
	v_sub_f32_e32 v11, v75, v136
	v_add_f32_e32 v10, v18, v10
	v_exp_f32_e32 v58, v11
	v_sub_f32_e32 v11, v76, v136
	v_add_f32_e32 v10, v19, v10
	v_exp_f32_e32 v59, v11
	v_sub_f32_e32 v11, v77, v136
	v_add_f32_e32 v10, v38, v10
	v_exp_f32_e32 v60, v11
	v_sub_f32_e32 v11, v78, v136
	v_add_f32_e32 v10, v39, v10
	v_exp_f32_e32 v61, v11
	v_sub_f32_e32 v11, v46, v136
	v_add_f32_e32 v10, v58, v10
	v_exp_f32_e32 v78, v11
	v_sub_f32_e32 v11, v47, v136
	v_add_f32_e32 v10, v59, v10
	v_exp_f32_e32 v79, v11
	v_sub_f32_e32 v11, v96, v136
	v_add_f32_e32 v10, v60, v10
	v_exp_f32_e32 v98, v11
	v_sub_f32_e32 v11, v97, v136
	v_add_f32_e32 v10, v61, v10
	v_exp_f32_e32 v99, v11
	v_sub_f32_e32 v11, v100, v136
	v_add_f32_e32 v10, v78, v10
	v_exp_f32_e32 v126, v11
	v_sub_f32_e32 v11, v101, v136
	v_add_f32_e32 v10, v79, v10
	v_exp_f32_e32 v127, v11
	v_sub_f32_e32 v11, v102, v136
	v_add_f32_e32 v10, v98, v10
	v_exp_f32_e32 v62, v11
	v_sub_f32_e32 v11, v103, v136
	v_add_f32_e32 v10, v99, v10
	v_exp_f32_e32 v63, v11
	v_sub_f32_e32 v11, v104, v136
	v_add_f32_e32 v10, v126, v10
	v_exp_f32_e32 v42, v11
	v_sub_f32_e32 v11, v105, v136
	v_add_f32_e32 v10, v127, v10
	v_exp_f32_e32 v43, v11
	v_sub_f32_e32 v11, v106, v136
	v_add_f32_e32 v10, v62, v10
	v_exp_f32_e32 v54, v11
	v_sub_f32_e32 v11, v107, v136
	v_add_f32_e32 v10, v63, v10
	v_exp_f32_e32 v55, v11
	v_sub_f32_e32 v11, v108, v136
	v_add_f32_e32 v10, v42, v10
	v_exp_f32_e32 v96, v11
	v_sub_f32_e32 v11, v109, v136
	v_add_f32_e32 v10, v43, v10
	v_exp_f32_e32 v97, v11
	v_sub_f32_e32 v11, v110, v136
	v_add_f32_e32 v10, v54, v10
	v_exp_f32_e32 v124, v11
	v_sub_f32_e32 v11, v111, v136
	v_add_f32_e32 v10, v55, v10
	v_exp_f32_e32 v125, v11
	v_sub_f32_e32 v11, v50, v136
	v_add_f32_e32 v10, v96, v10
	v_exp_f32_e32 v50, v11
	v_sub_f32_e32 v11, v51, v136
	v_add_f32_e32 v10, v97, v10
	v_exp_f32_e32 v51, v11
	v_sub_f32_e32 v11, v20, v136
	v_add_f32_e32 v10, v124, v10
	v_exp_f32_e32 v76, v11
	v_sub_f32_e32 v11, v21, v136
	v_add_f32_e32 v10, v125, v10
	v_exp_f32_e32 v77, v11
	v_sub_f32_e32 v11, v22, v136
	v_add_f32_e32 v10, v50, v10
	v_exp_f32_e32 v52, v11
	v_sub_f32_e32 v11, v23, v136
	v_add_f32_e32 v10, v51, v10
	v_exp_f32_e32 v53, v11
	v_sub_f32_e32 v11, v24, v136
	v_add_f32_e32 v10, v76, v10
	v_exp_f32_e32 v56, v11
	v_sub_f32_e32 v11, v25, v136
	v_add_f32_e32 v10, v77, v10
	v_exp_f32_e32 v57, v11
	v_sub_f32_e32 v11, v26, v136
	v_add_f32_e32 v10, v52, v10
	v_exp_f32_e32 v40, v11
	v_sub_f32_e32 v11, v27, v136
	v_add_f32_e32 v10, v53, v10
	v_exp_f32_e32 v41, v11
	v_sub_f32_e32 v11, v28, v136
	v_add_f32_e32 v10, v56, v10
	v_exp_f32_e32 v46, v11
	v_sub_f32_e32 v11, v29, v136
	v_add_f32_e32 v10, v57, v10
	v_exp_f32_e32 v47, v11
	v_sub_f32_e32 v11, v30, v136
	v_add_f32_e32 v10, v40, v10
	v_exp_f32_e32 v112, v11
	v_sub_f32_e32 v11, v31, v136
	v_add_f32_e32 v10, v41, v10
	v_exp_f32_e32 v113, v11
	v_sub_f32_e32 v11, v32, v136
	v_add_f32_e32 v10, v46, v10
	v_exp_f32_e32 v118, v11
	v_sub_f32_e32 v11, v33, v136
	v_add_f32_e32 v10, v47, v10
	v_exp_f32_e32 v119, v11
	v_add_f32_e32 v10, v112, v10
	v_add_f32_e32 v10, v113, v10
	v_add_f32_e32 v10, v118, v10
	v_add_f32_e32 v20, v119, v10
	v_sub_f32_e32 v10, v114, v136
	v_exp_f32_e32 v64, v10
	v_sub_f32_e32 v10, v115, v136
	v_sub_f32_e32 v21, v116, v136
	v_exp_f32_e32 v65, v10
	global_load_dwordx4 v[10:13], v[48:49], off
	v_exp_f32_e32 v72, v21
	v_sub_f32_e32 v21, v117, v136
	v_exp_f32_e32 v73, v21
	v_sub_f32_e32 v21, v120, v136
	v_exp_f32_e32 v66, v21
	v_sub_f32_e32 v21, v121, v136
	v_exp_f32_e32 v67, v21
	v_sub_f32_e32 v21, v122, v136
	v_exp_f32_e32 v74, v21
	v_sub_f32_e32 v21, v123, v136
	v_exp_f32_e32 v75, v21
	v_sub_f32_e32 v21, v132, v136
	v_exp_f32_e32 v68, v21
	v_sub_f32_e32 v21, v133, v136
	v_exp_f32_e32 v69, v21
	v_sub_f32_e32 v21, v134, v136
	v_exp_f32_e32 v70, v21
	v_sub_f32_e32 v21, v135, v136
	global_load_dwordx4 v[132:135], v[48:49], off offset:2048
	v_add_f32_e32 v20, v64, v20
	v_add_f32_e32 v20, v65, v20
	v_add_f32_e32 v20, v72, v20
	v_add_f32_e32 v20, v73, v20
	v_add_f32_e32 v20, v66, v20
	v_add_f32_e32 v20, v67, v20
	v_add_f32_e32 v20, v74, v20
	v_add_f32_e32 v20, v75, v20
	v_exp_f32_e32 v71, v21
	v_sub_f32_e32 v14, v14, v136
	v_add_f32_e32 v20, v68, v20
	v_exp_f32_e32 v102, v14
	v_sub_f32_e32 v14, v15, v136
	v_add_f32_e32 v20, v69, v20
	v_exp_f32_e32 v103, v14
	v_sub_f32_e32 v14, v16, v136
	v_add_f32_e32 v20, v70, v20
	v_exp_f32_e32 v106, v14
	v_sub_f32_e32 v14, v17, v136
	v_add_f32_e32 v20, v71, v20
	v_exp_f32_e32 v107, v14
	v_add_f32_e32 v14, v102, v20
	v_add_f32_e32 v14, v103, v14
	v_add_f32_e32 v14, v106, v14
	v_add_f32_e32 v14, v107, v14
	ds_bpermute_b32 v15, v205, v14
	global_load_dwordx4 v[20:23], v[48:49], off offset:1024
	global_load_dwordx4 v[136:139], v[48:49], off offset:3072
	s_waitcnt lgkmcnt(0)
	v_add_f32_e32 v14, v14, v15
	v_max_f32_e32 v14, 0xda24260, v14
	v_div_scale_f32 v15, s[0:1], v14, v14, 1.0
	v_rcp_f32_e32 v16, v15
	s_nop 0
	v_fma_f32 v17, -v15, v16, 1.0
	v_fmac_f32_e32 v16, v17, v16
	v_div_scale_f32 v17, vcc, 1.0, v14, 1.0
	v_mul_f32_e32 v24, v17, v16
	v_fma_f32 v25, -v15, v24, v17
	v_fmac_f32_e32 v24, v25, v16
	v_fma_f32 v15, -v15, v24, v17
	v_div_fmas_f32 v15, v15, v16, v24
	v_div_fixup_f32 v156, v15, v14, 1.0
	v_pk_mul_f32 v[120:121], v[2:3], v[156:157] op_sel_hi:[1,0]
	v_pk_mul_f32 v[122:123], v[4:5], v[156:157] op_sel_hi:[1,0]
	v_pk_mul_f32 v[110:111], v[6:7], v[156:157] op_sel_hi:[1,0]
	v_pk_mul_f32 v[116:117], v[8:9], v[156:157] op_sel_hi:[1,0]
	v_cvt_pk_bf16_f32 v24, v120, v121
	v_cvt_pk_bf16_f32 v25, v122, v123
	v_cvt_pk_bf16_f32 v26, v110, v111
	v_cvt_pk_bf16_f32 v27, v116, v117
	v_add_co_u32_e32 v158, vcc, s2, v48
	s_nop 1
	v_addc_co_u32_e32 v159, vcc, 0, v49, vcc
	global_load_dwordx4 v[140:143], v[158:159], off offset:-4096
	global_load_dwordx4 v[210:213], v[158:159], off offset:-3072
	global_load_dwordx4 v[218:221], v[158:159], off offset:-2048
	global_load_dwordx4 v[222:225], v[158:159], off offset:-1024
	global_load_dwordx4 v[214:217], v[158:159], off
	global_load_dwordx4 v[184:187], v[158:159], off offset:1024
	global_load_dwordx4 v[230:233], v[158:159], off offset:2048
	global_load_dwordx4 v[192:195], v[158:159], off offset:3072
	global_load_dwordx4 v[226:229], v[44:45], off
	s_waitcnt vmcnt(12)
	v_mfma_f32_32x32x16_bf16 v[2:17], v[10:13], v[24:27], 0
	v_mul_f32_e64 v108, v18, v156
	v_mul_f32_e64 v109, v19, v156
	v_mul_f32_e64 v114, v38, v156
	v_mul_f32_e64 v115, v39, v156
	v_pk_mul_f32 v[100:101], v[58:59], v[156:157] op_sel_hi:[1,0]
	v_pk_mul_f32 v[104:105], v[60:61], v[156:157] op_sel_hi:[1,0]
	v_add_co_u32_e32 v160, vcc, s3, v48
	v_cvt_pk_bf16_f32 v144, v108, v109
	v_cvt_pk_bf16_f32 v145, v114, v115
	v_cvt_pk_bf16_f32 v146, v100, v101
	v_cvt_pk_bf16_f32 v147, v104, v105
	v_addc_co_u32_e32 v161, vcc, 0, v49, vcc
	s_waitcnt vmcnt(11)
	v_mfma_f32_32x32x16_bf16 v[2:17], v[132:135], v[144:147], v[2:17]
	v_mul_f32_e64 v58, v78, v156
	v_mul_f32_e64 v59, v79, v156
	v_mul_f32_e64 v60, v98, v156
	v_mul_f32_e64 v61, v99, v156
	v_pk_mul_f32 v[38:39], v[126:127], v[156:157] op_sel_hi:[1,0]
	v_pk_mul_f32 v[62:63], v[62:63], v[156:157] op_sel_hi:[1,0]
	v_pk_mul_f32 v[78:79], v[42:43], v[156:157] op_sel_hi:[1,0]
	v_pk_mul_f32 v[98:99], v[54:55], v[156:157] op_sel_hi:[1,0]
	s_waitcnt vmcnt(10)
	v_mfma_f32_32x32x16_bf16 v[18:33], v[20:23], v[24:27], 0
	v_mul_f32_e64 v42, v96, v156
	v_mul_f32_e64 v43, v97, v156
	v_mul_f32_e64 v48, v124, v156
	v_mul_f32_e64 v49, v125, v156
	v_cvt_pk_bf16_f32 v124, v78, v79
	v_cvt_pk_bf16_f32 v125, v98, v99
	v_cvt_pk_bf16_f32 v126, v42, v43
	v_cvt_pk_bf16_f32 v127, v48, v49
	v_pk_mul_f32 v[50:51], v[50:51], v[156:157] op_sel_hi:[1,0]
	s_waitcnt vmcnt(9)
	v_mfma_f32_32x32x16_bf16 v[18:33], v[136:139], v[144:147], v[18:33]
	v_cvt_pk_bf16_f32 v136, v58, v59
	v_cvt_pk_bf16_f32 v137, v60, v61
	v_cvt_pk_bf16_f32 v138, v38, v39
	v_cvt_pk_bf16_f32 v139, v62, v63
	v_pk_mul_f32 v[54:55], v[76:77], v[156:157] op_sel_hi:[1,0]
	v_pk_mul_f32 v[52:53], v[52:53], v[156:157] op_sel_hi:[1,0]
	s_waitcnt vmcnt(8)
	v_mfma_f32_32x32x16_bf16 v[2:17], v[140:143], v[136:139], v[2:17]
	global_load_dwordx4 v[140:143], v[44:45], off offset:1024
	v_mul_f32_e64 v56, v56, v156
	v_mul_f32_e64 v57, v57, v156
	v_mul_f32_e64 v76, v40, v156
	v_mul_f32_e64 v77, v41, v156
	v_pk_mul_f32 v[96:97], v[46:47], v[156:157] op_sel_hi:[1,0]
	v_pk_mul_f32 v[40:41], v[112:113], v[156:157] op_sel_hi:[1,0]
	v_pk_mul_f32 v[46:47], v[118:119], v[156:157] op_sel_hi:[1,0]
	v_pk_mul_f32 v[64:65], v[64:65], v[156:157] op_sel_hi:[1,0]
	s_waitcnt vmcnt(8)
	v_mfma_f32_32x32x16_bf16 v[18:33], v[210:213], v[136:139], v[18:33]
	global_load_dwordx4 v[210:213], v[44:45], off offset:2048
	v_mul_f32_e64 v72, v72, v156
	v_mul_f32_e64 v73, v73, v156
	v_mul_f32_e64 v66, v66, v156
	v_mul_f32_e64 v67, v67, v156
	v_pk_mul_f32 v[74:75], v[74:75], v[156:157] op_sel_hi:[1,0]
	v_pk_mul_f32 v[112:113], v[68:69], v[156:157] op_sel_hi:[1,0]
	v_pk_mul_f32 v[70:71], v[70:71], v[156:157] op_sel_hi:[1,0]
	s_waitcnt vmcnt(8)
	v_mfma_f32_32x32x16_bf16 v[2:17], v[218:221], v[124:127], v[2:17]
	v_mul_f32_e64 v68, v106, v156
	v_mul_f32_e64 v69, v107, v156
	s_waitcnt vmcnt(7)
	v_mfma_f32_32x32x16_bf16 v[18:33], v[222:225], v[124:127], v[18:33]
	v_cvt_pk_bf16_f32 v132, v50, v51
	v_cvt_pk_bf16_f32 v133, v54, v55
	v_cvt_pk_bf16_f32 v134, v52, v53
	v_cvt_pk_bf16_f32 v135, v56, v57
	s_nop 1
	s_waitcnt vmcnt(6)
	v_mfma_f32_32x32x16_bf16 v[2:17], v[214:217], v[132:135], v[2:17]
	s_waitcnt vmcnt(5)
	v_mfma_f32_32x32x16_bf16 v[18:33], v[184:187], v[132:135], v[18:33]
	v_cvt_pk_bf16_f32 v124, v76, v77
	v_cvt_pk_bf16_f32 v125, v96, v97
	v_cvt_pk_bf16_f32 v126, v40, v41
	v_cvt_pk_bf16_f32 v127, v46, v47
	s_nop 1
	s_waitcnt vmcnt(4)
	v_mfma_f32_32x32x16_bf16 v[2:17], v[230:233], v[124:127], v[2:17]
	s_waitcnt vmcnt(3)
	v_mfma_f32_32x32x16_bf16 v[18:33], v[192:195], v[124:127], v[18:33]
	v_cvt_pk_bf16_f32 v132, v64, v65
	v_cvt_pk_bf16_f32 v133, v72, v73
	v_cvt_pk_bf16_f32 v134, v66, v67
	v_cvt_pk_bf16_f32 v135, v74, v75
	s_nop 1
	s_waitcnt vmcnt(2)
	v_mfma_f32_32x32x16_bf16 v[2:17], v[226:229], v[132:135], v[2:17]
	v_mul_f32_e64 v44, v102, v156
	v_mul_f32_e64 v45, v103, v156
	s_waitcnt vmcnt(1)
	v_mfma_f32_32x32x16_bf16 v[18:33], v[140:143], v[132:135], v[18:33]
	v_cvt_pk_bf16_f32 v124, v112, v113
	v_cvt_pk_bf16_f32 v125, v70, v71
	v_cvt_pk_bf16_f32 v126, v44, v45
	v_cvt_pk_bf16_f32 v127, v68, v69
	s_waitcnt vmcnt(0)
	s_nop 0
	v_mfma_f32_32x32x16_bf16 v[2:17], v[210:213], v[124:127], v[2:17]
	v_mfma_f32_32x32x16_bf16 v[18:33], v[34:37], v[124:127], v[18:33]
	s_nop 10
	v_mul_f32_e32 v2, v0, v2
	v_mul_f32_e32 v3, v0, v3
	ds_write2st64_b32 v206, v2, v3 offset0:4 offset1:5
	v_mul_f32_e32 v18, v0, v18
	v_mul_f32_e32 v2, v0, v19
	ds_write2st64_b32 v206, v18, v2 offset0:20 offset1:21
	v_mul_f32_e32 v2, v0, v4
	v_mul_f32_e32 v4, v0, v5
	v_mul_f32_e32 v3, v0, v20
	ds_write2st64_b32 v206, v2, v4 offset0:6 offset1:7
	v_mul_f32_e32 v2, v0, v21
	ds_write2st64_b32 v206, v3, v2 offset0:22 offset1:23
	v_mul_f32_e32 v2, v0, v6
	v_mul_f32_e32 v4, v0, v7
	v_mul_f32_e32 v3, v0, v22
	ds_write2st64_b32 v206, v2, v4 offset0:8 offset1:9
	v_mul_f32_e32 v2, v0, v23
	ds_write2st64_b32 v206, v3, v2 offset0:24 offset1:25
	v_mul_f32_e32 v2, v0, v8
	v_mul_f32_e32 v4, v0, v9
	v_mul_f32_e32 v3, v0, v24
	ds_write2st64_b32 v206, v2, v4 offset0:10 offset1:11
	v_mul_f32_e32 v2, v0, v25
	ds_write2st64_b32 v206, v3, v2 offset0:26 offset1:27
	v_mul_f32_e32 v2, v0, v10
	v_mul_f32_e32 v4, v0, v11
	v_mul_f32_e32 v3, v0, v26
	ds_write2st64_b32 v206, v2, v4 offset0:12 offset1:13
	v_mul_f32_e32 v2, v0, v27
	ds_write2st64_b32 v206, v3, v2 offset0:28 offset1:29
	v_mul_f32_e32 v2, v0, v12
	v_mul_f32_e32 v4, v0, v13
	v_mul_f32_e32 v3, v0, v28
	ds_write2st64_b32 v206, v2, v4 offset0:14 offset1:15
	v_mul_f32_e32 v2, v0, v29
	ds_write2st64_b32 v206, v3, v2 offset0:30 offset1:31
	v_mul_f32_e32 v2, v0, v14
	v_mul_f32_e32 v4, v0, v15
	v_mul_f32_e32 v3, v0, v30
	ds_write2st64_b32 v206, v2, v4 offset0:16 offset1:17
	v_mul_f32_e32 v2, v0, v31
	ds_bpermute_b32 v20, v205, v123
	ds_write2st64_b32 v206, v3, v2 offset0:32 offset1:33
	v_mul_f32_e32 v2, v0, v16
	v_mul_f32_e32 v3, v0, v32
	v_mul_f32_e32 v4, v0, v17
	v_mul_f32_e32 v0, v0, v33
	ds_write2st64_b32 v206, v3, v0 offset0:34 offset1:35
	v_xor_b32_e32 v3, 1, v235
	v_cmp_lt_i32_e32 vcc, v3, v131
	ds_write2st64_b32 v206, v2, v4 offset0:18 offset1:19
	v_add_f32_e32 v4, v122, v123
	v_cndmask_b32_e32 v3, v235, v3, vcc
	v_add_f32_e32 v6, v120, v121
	v_cmp_gt_u32_e32 vcc, 32, v188
	v_add_f32_e32 v4, v6, v4
	v_lshlrev_b32_e32 v3, 2, v3
	s_waitcnt lgkmcnt(3)
	v_cndmask_b32_e64 v6, v20, 0, vcc
	v_add_f32_e32 v4, v6, v4
	s_nop 1
	v_mov_b32_dpp v6, v4 quad_perm:[1,0,3,2] row_mask:0xf bank_mask:0xf
	v_xor_b32_e32 v7, 2, v235
	v_cmp_lt_i32_e64 s[0:1], v7, v131
	ds_bpermute_b32 v19, v205, v117
	ds_bpermute_b32 v18, v205, v115
	v_cndmask_b32_e64 v7, v235, v7, s[0:1]
	v_lshlrev_b32_e32 v7, 2, v7
	s_waitcnt lgkmcnt(2)
	v_add_f32_e32 v21, v4, v6
	ds_bpermute_b32 v17, v205, v105
	ds_bpermute_b32 v16, v205, v61
	ds_bpermute_b32 v15, v205, v63
	ds_bpermute_b32 v14, v205, v99
	ds_bpermute_b32 v13, v205, v49
	ds_bpermute_b32 v12, v205, v55
	ds_bpermute_b32 v11, v205, v57
	ds_bpermute_b32 v10, v205, v97
	ds_bpermute_b32 v9, v205, v47
	ds_bpermute_b32 v8, v205, v73
	ds_bpermute_b32 v5, v205, v75
	ds_bpermute_b32 v0, v205, v71
	ds_bpermute_b32 v2, v205, v69
	s_nop 1
	v_mov_b32_dpp v22, v21 quad_perm:[2,3,0,1] row_mask:0xf bank_mask:0xf
	v_lshlrev_b32_e32 v4, 5, v129
	v_add_u32_e32 v6, v4, v196
	v_lshl_add_u32 v6, v6, 2, s83
	s_and_saveexec_b64 s[0:1], s[8:9]
	s_cbranch_execz .LBB0_1568
	s_waitcnt lgkmcnt(0)
	v_add_f32_e32 v21, v21, v22
	ds_write_b32 v6, v21
